# adds: v_rsq in RWKV post-chunk groupnorm; prep_even (P3) lora activations branch-free (same tanh formulas, no divergent exec regions)
# speedup vs baseline: 1.0350x; 1.0150x over previous
; __device__ __forceinline__ int lane_id_() { int l; asm volatile("v_mbcnt_lo_u32_b32 %0, -1, 0\n\tv_mbcnt_hi_u32_b32 %0, -1, %0" : "=v"(l)); return l; }
; __device__ __forceinline__ void prep_even_phase(const Ctx& F) {
;     const bf16_t* proj = (const bf16_t*)(F.ws + WS_BIG);
;     float* stats = (float*)(F.ws + WS_STATS); float* cs = (float*)(F.ws + WS_CS);
;     bf16_t* KR = (bf16_t*)(F.ws + WS_KR); bf16_t* AP = (bf16_t*)(F.ws + WS_AP);
;     const int gw = F.bid * NWAVES + F.wid, NGW = F.G * NWAVES, lane = lane_id_();
;     const int l32 = lane & 31;
;     float mu8[8];
;     { const f32x4 m0 = *(const f32x4*)(F_mu + 1536 + 8 * l32), m1 = *(const f32x4*)(F_mu + 1536 + 8 * l32 + 4); mu8[0] = m0[0]; mu8[1] = m0[1]; mu8[2] = m0[2]; mu8[3] = m0[3]; mu8[4] = m1[0]; mu8[5] = m1[1]; mu8[6] = m1[2]; mu8[7] = m1[3]; }
;     const float inv = __builtin_amdgcn_exp2f(-13.287712379549449f * ((float)(lane & 15) * (1.0f / 16.0f)));
;     const u32x4 z4 = {0u, 0u, 0u, 0u};
;     for (int ch = gw; ch < T / 4; ch += NGW) {
;         u32x4 rq[4], rkv[4], rc[4], rpv[4]; bf16_t kr[4][2]; int ps[4];
; #pragma unroll
.LBB0_295:
	s_cmp_lt_i32 s84, 4
	s_cselect_b64 s[0:1], -1, 0
	s_cmp_gt_i32 s85, 3
	s_cselect_b64 s[4:5], -1, 0
	s_and_b64 s[0:1], s[0:1], s[4:5]
	s_andn2_b64 vcc, exec, s[0:1]
	s_cbranch_vccnz .LBB0_652
	s_lshl_b32 s0, s2, 3
	s_add_i32 s0, s50, s0
	s_mov_b64 s[4:5], s[88:89]
	s_cmpk_lt_i32 s0, 0x4000
	v_mbcnt_lo_u32_b32 v8, -1, 0
	v_mbcnt_hi_u32_b32 v8, -1, v8
	s_cbranch_scc0 .LBB0_596
	s_load_dwordx2 s[6:7], s[4:5], 0x60
	s_load_dwordx2 s[18:19], s[4:5], 0x10
	v_lshlrev_b32_e32 v72, 3, v8
	v_and_b32_e32 v10, 0xf8, v72
	v_mov_b32_e32 v75, 0
	v_lshlrev_b32_e32 v74, 2, v10
	s_waitcnt lgkmcnt(0)
	v_lshl_add_u64 v[0:1], s[6:7], 0, v[74:75]
	v_add_co_u32_e32 v14, vcc, 0x1000, v0
	s_mov_b64 s[4:5], 0x1800
	s_nop 0
	v_addc_co_u32_e32 v15, vcc, 0, v1, vcc
	v_lshl_add_u64 v[12:13], v[0:1], 0, s[4:5]
	flat_load_dwordx4 v[0:3], v[14:15] offset:2048
	flat_load_dwordx4 v[4:7], v[12:13] offset:16
	v_and_b32_e32 v76, 15, v8
	v_cvt_f32_ubyte0_e32 v9, v76
	v_mul_f32_e32 v9, 0x3d800000, v9
	v_mul_f32_e32 v9, 0xc1549a78, v9
	v_exp_f32_e32 v77, v9
	v_ashrrev_i32_e32 v9, 31, v8
	v_ashrrev_i32_e32 v73, 31, v72
	v_lshl_add_u64 v[12:13], v[8:9], 1, s[46:47]
	s_mov_b64 s[12:13], 0x2a200000
	v_lshl_add_u64 v[78:79], v[12:13], 0, s[12:13]
	v_lshl_add_u64 v[12:13], v[72:73], 1, s[46:47]
	s_mov_b64 s[16:17], 0x30200000
	s_add_u32 s1, s46, 0x3900000
	v_cmp_gt_i32_e64 s[4:5], 48, v8
	v_cmp_eq_u32_e64 s[6:7], 0, v8
	v_cmp_gt_i32_e64 s[8:9], 16, v8
	v_cmp_gt_i32_e64 s[10:11], 32, v8
	v_cmp_lt_i32_e64 s[12:13], 7, v8
	v_cmp_lt_u32_e64 s[14:15], 15, v8
	v_lshl_add_u64 v[80:81], v[12:13], 0, s[16:17]
	v_lshl_add_u64 v[8:9], v[8:9], 2, s[46:47]
	s_mov_b64 s[16:17], 0x3a00000
	s_addc_u32 s3, s47, 0
	v_lshl_add_u64 v[82:83], v[8:9], 0, s[16:17]
	s_lshl_b32 s16, s2, 6
	s_lshl_b32 s17, s50, 3
	s_add_i32 s20, s16, s17
	s_lshl_b32 s16, s2, 5
	s_lshl_b32 s17, s50, 2
	s_mov_b32 s26, 0x6dc9c883
	s_lshl_b32 s33, s90, 3
	s_lshl_b32 s40, s90, 6
	s_add_i32 s22, s16, s17
	s_lshl_b32 s41, s90, 5
	v_lshlrev_b32_e32 v74, 1, v10
	s_mov_b64 s[24:25], 0x1140
	v_mov_b32_e32 v84, 0x358637bd
	s_mov_b32 s43, 0xf800000
	v_mov_b32_e32 v85, 0x260
	s_mov_b32 s27, 0x3fc45f30
	s_mov_b32 s48, 0x3f200000
	s_mov_b32 s49, 0x3fb8aa3b
	s_mov_b32 s51, 0xc2ce8ed0
	s_mov_b32 s54, 0x42b17218
	v_mov_b32_e32 v86, 0x3ca908c9
	s_brev_b32 s55, -2
	v_mov_b32_e32 v87, 0x7f800000
	v_mbcnt_lo_u32_b32 v104, -1, 0
	v_mbcnt_hi_u32_b32 v104, -1, v104
	v_cmp_gt_u32_e32 vcc, 8, v104
	v_mov_b32_e32 v105, 0xbfb8aa3b
	v_mov_b32_e32 v107, 0x4038aa3b
	v_mov_b32_e32 v106, -1
	v_cndmask_b32_e32 v105, v105, v107, vcc
	v_bfrev_b32_e32 v107, -2
	v_cndmask_b32_e32 v106, v106, v107, vcc
	s_branch .LBB0_301

; __device__ __forceinline__ unsigned pk2(float lo, float hi) { f32x2 v = {lo, hi}; bf16x2_t b = __builtin_convertvector(v, bf16x2_t); return __builtin_bit_cast(unsigned, b); }
; __device__ __forceinline__ float sigmoidf_(float x) { return __builtin_amdgcn_rcpf(1.f + __expf(-x)); }
; __device__ __forceinline__ void prep_even_phase(const Ctx& F) {
;     ...
;             if (lane < 32) {
;                 float cu[8], pv[8], o[8]; unpack8(rc[u], cu); unpack8(rpv[u], pv);
; #pragma unroll
;                 for (int e = 0; e < 8; ++e) { float v = cu[e] + (pv[e] - cu[e]) * mu8[e]; if (lane < 8) v = tanhf(v); else if (lane >= 16) v = sigmoidf_(v); o[e] = v; }
;                 *(u32x4*)(AP + (size_t)row * 256 + 8 * lane) = (u32x4){pk2(o[0], o[1]), pk2(o[2], o[3]), pk2(o[4], o[5]), pk2(o[6], o[7])};
;             }
.LBB0_323:
	s_waitcnt lgkmcnt(0)
	v_lshlrev_b32_e32 v108, 16, v56
	v_lshlrev_b32_e32 v109, 16, v60
	v_sub_f32_e32 v109, v109, v108
	v_fmac_f32_e32 v108, v0, v109
	v_and_b32_e32 v110, v106, v108
	v_mul_f32_e32 v110, v105, v110
	v_exp_f32_e32 v110, v110
	v_mul_f32_e32 v111, v108, v108
	v_add_f32_e32 v110, 1.0, v110
	v_rcp_f32_e32 v110, v110
	v_fmamk_f32 v112, v111, 0xbbbac73d, v86
	v_fmaak_f32 v112, v111, v112, 0xbd5c1c4e
	v_fmaak_f32 v112, v111, v112, 0x3e088382
	v_fmaak_f32 v112, v111, v112, 0xbeaaaa99
	v_mul_f32_e64 v112, |v108|, v112
	v_fma_f32 v112, v111, v112, |v108|
	v_fma_f32 v113, v110, -2.0, 1.0
	v_cmp_lt_f32_e64 vcc, |v108|, s48
	v_cndmask_b32_e64 v110, v108, v110, s[14:15]
	s_nop 0
	v_cndmask_b32_e32 v113, v113, v112, vcc
	v_bfi_b32 v113, s55, v113, v108
	v_cndmask_b32_e64 v120, v113, v110, s[12:13]
	v_and_b32_e32 v114, 0xffff0000, v56
	v_and_b32_e32 v115, 0xffff0000, v60
	v_sub_f32_e32 v115, v115, v114
	v_fmac_f32_e32 v114, v1, v115
	v_and_b32_e32 v116, v106, v114
	v_mul_f32_e32 v116, v105, v116
	v_exp_f32_e32 v116, v116
	v_mul_f32_e32 v117, v114, v114
	v_add_f32_e32 v116, 1.0, v116
	v_rcp_f32_e32 v116, v116
	v_fmamk_f32 v118, v117, 0xbbbac73d, v86
	v_fmaak_f32 v118, v117, v118, 0xbd5c1c4e
	v_fmaak_f32 v118, v117, v118, 0x3e088382
	v_fmaak_f32 v118, v117, v118, 0xbeaaaa99
	v_mul_f32_e64 v118, |v114|, v118
	v_fma_f32 v118, v117, v118, |v114|
	v_fma_f32 v119, v116, -2.0, 1.0
	v_cmp_lt_f32_e64 vcc, |v114|, s48
	v_cndmask_b32_e64 v116, v114, v116, s[14:15]
	s_nop 0
	v_cndmask_b32_e32 v119, v119, v118, vcc
	v_bfi_b32 v119, s55, v119, v114
	v_cndmask_b32_e64 v121, v119, v116, s[12:13]
	v_lshlrev_b32_e32 v108, 16, v57
	v_lshlrev_b32_e32 v109, 16, v61
	v_sub_f32_e32 v109, v109, v108
	v_fmac_f32_e32 v108, v2, v109
	v_and_b32_e32 v110, v106, v108
	v_mul_f32_e32 v110, v105, v110
	v_exp_f32_e32 v110, v110
	v_mul_f32_e32 v111, v108, v108
	v_add_f32_e32 v110, 1.0, v110
	v_rcp_f32_e32 v110, v110
	v_fmamk_f32 v112, v111, 0xbbbac73d, v86
	v_fmaak_f32 v112, v111, v112, 0xbd5c1c4e
	v_fmaak_f32 v112, v111, v112, 0x3e088382
	v_fmaak_f32 v112, v111, v112, 0xbeaaaa99
	v_mul_f32_e64 v112, |v108|, v112
	v_fma_f32 v112, v111, v112, |v108|
	v_fma_f32 v113, v110, -2.0, 1.0
	v_cmp_lt_f32_e64 vcc, |v108|, s48
	v_cndmask_b32_e64 v110, v108, v110, s[14:15]
	s_nop 0
	v_cndmask_b32_e32 v113, v113, v112, vcc
	v_bfi_b32 v113, s55, v113, v108
	v_cndmask_b32_e64 v122, v113, v110, s[12:13]
	v_and_b32_e32 v114, 0xffff0000, v57
	v_and_b32_e32 v115, 0xffff0000, v61
	v_sub_f32_e32 v115, v115, v114
	v_fmac_f32_e32 v114, v3, v115
	v_and_b32_e32 v116, v106, v114
	v_mul_f32_e32 v116, v105, v116
	v_exp_f32_e32 v116, v116
	v_mul_f32_e32 v117, v114, v114
	v_add_f32_e32 v116, 1.0, v116
	v_rcp_f32_e32 v116, v116
	v_fmamk_f32 v118, v117, 0xbbbac73d, v86
	v_fmaak_f32 v118, v117, v118, 0xbd5c1c4e
	v_fmaak_f32 v118, v117, v118, 0x3e088382
	v_fmaak_f32 v118, v117, v118, 0xbeaaaa99
	v_mul_f32_e64 v118, |v114|, v118
	v_fma_f32 v118, v117, v118, |v114|
	v_fma_f32 v119, v116, -2.0, 1.0
	v_cmp_lt_f32_e64 vcc, |v114|, s48
	v_cndmask_b32_e64 v116, v114, v116, s[14:15]
	s_nop 0
	v_cndmask_b32_e32 v119, v119, v118, vcc
	v_bfi_b32 v119, s55, v119, v114
	v_cndmask_b32_e64 v123, v119, v116, s[12:13]
	v_lshlrev_b32_e32 v108, 16, v58
	v_lshlrev_b32_e32 v109, 16, v62
	v_sub_f32_e32 v109, v109, v108
	v_fmac_f32_e32 v108, v4, v109
	v_and_b32_e32 v110, v106, v108
	v_mul_f32_e32 v110, v105, v110
	v_exp_f32_e32 v110, v110
	v_mul_f32_e32 v111, v108, v108
	v_add_f32_e32 v110, 1.0, v110
	v_rcp_f32_e32 v110, v110
	v_fmamk_f32 v112, v111, 0xbbbac73d, v86
	v_fmaak_f32 v112, v111, v112, 0xbd5c1c4e
	v_fmaak_f32 v112, v111, v112, 0x3e088382
	v_fmaak_f32 v112, v111, v112, 0xbeaaaa99
	v_mul_f32_e64 v112, |v108|, v112
	v_fma_f32 v112, v111, v112, |v108|
	v_fma_f32 v113, v110, -2.0, 1.0
	v_cmp_lt_f32_e64 vcc, |v108|, s48
	v_cndmask_b32_e64 v110, v108, v110, s[14:15]
	s_nop 0
	v_cndmask_b32_e32 v113, v113, v112, vcc
	v_bfi_b32 v113, s55, v113, v108
	v_cndmask_b32_e64 v124, v113, v110, s[12:13]
	v_and_b32_e32 v114, 0xffff0000, v58
	v_and_b32_e32 v115, 0xffff0000, v62
	v_sub_f32_e32 v115, v115, v114
	v_fmac_f32_e32 v114, v5, v115
	v_and_b32_e32 v116, v106, v114
	v_mul_f32_e32 v116, v105, v116
	v_exp_f32_e32 v116, v116
	v_mul_f32_e32 v117, v114, v114
	v_add_f32_e32 v116, 1.0, v116
	v_rcp_f32_e32 v116, v116
	v_fmamk_f32 v118, v117, 0xbbbac73d, v86
	v_fmaak_f32 v118, v117, v118, 0xbd5c1c4e
	v_fmaak_f32 v118, v117, v118, 0x3e088382
	v_fmaak_f32 v118, v117, v118, 0xbeaaaa99
	v_mul_f32_e64 v118, |v114|, v118
	v_fma_f32 v118, v117, v118, |v114|
	v_fma_f32 v119, v116, -2.0, 1.0
	v_cmp_lt_f32_e64 vcc, |v114|, s48
	v_cndmask_b32_e64 v116, v114, v116, s[14:15]
	s_nop 0
	v_cndmask_b32_e32 v119, v119, v118, vcc
	v_bfi_b32 v119, s55, v119, v114
	v_cndmask_b32_e64 v125, v119, v116, s[12:13]
	v_lshlrev_b32_e32 v108, 16, v59
	v_lshlrev_b32_e32 v109, 16, v63
	v_sub_f32_e32 v109, v109, v108
	v_fmac_f32_e32 v108, v6, v109
	v_and_b32_e32 v110, v106, v108
	v_mul_f32_e32 v110, v105, v110
	v_exp_f32_e32 v110, v110
	v_mul_f32_e32 v111, v108, v108
	v_add_f32_e32 v110, 1.0, v110
	v_rcp_f32_e32 v110, v110
	v_fmamk_f32 v112, v111, 0xbbbac73d, v86
	v_fmaak_f32 v112, v111, v112, 0xbd5c1c4e
	v_fmaak_f32 v112, v111, v112, 0x3e088382
	v_fmaak_f32 v112, v111, v112, 0xbeaaaa99
	v_mul_f32_e64 v112, |v108|, v112
	v_fma_f32 v112, v111, v112, |v108|
	v_fma_f32 v113, v110, -2.0, 1.0
	v_cmp_lt_f32_e64 vcc, |v108|, s48
	v_cndmask_b32_e64 v110, v108, v110, s[14:15]
	s_nop 0
	v_cndmask_b32_e32 v113, v113, v112, vcc
	v_bfi_b32 v113, s55, v113, v108
	v_cndmask_b32_e64 v126, v113, v110, s[12:13]
	v_and_b32_e32 v114, 0xffff0000, v59
	v_and_b32_e32 v115, 0xffff0000, v63
	v_sub_f32_e32 v115, v115, v114
	v_fmac_f32_e32 v114, v7, v115
	v_and_b32_e32 v116, v106, v114
	v_mul_f32_e32 v116, v105, v116
	v_exp_f32_e32 v116, v116
	v_mul_f32_e32 v117, v114, v114
	v_add_f32_e32 v116, 1.0, v116
	v_rcp_f32_e32 v116, v116
	v_fmamk_f32 v118, v117, 0xbbbac73d, v86
	v_fmaak_f32 v118, v117, v118, 0xbd5c1c4e
	v_fmaak_f32 v118, v117, v118, 0x3e088382
	v_fmaak_f32 v118, v117, v118, 0xbeaaaa99
	v_mul_f32_e64 v118, |v114|, v118
	v_fma_f32 v118, v117, v118, |v114|
	v_fma_f32 v119, v116, -2.0, 1.0
	v_cmp_lt_f32_e64 vcc, |v114|, s48
	v_cndmask_b32_e64 v116, v114, v116, s[14:15]
	s_nop 0
	v_cndmask_b32_e32 v119, v119, v118, vcc
	v_bfi_b32 v119, s55, v119, v114
	v_cndmask_b32_e64 v127, v119, v116, s[12:13]
	v_cvt_pk_bf16_f32 v56, v120, v121
	v_cvt_pk_bf16_f32 v57, v122, v123
	v_cvt_pk_bf16_f32 v58, v124, v125
	v_cvt_pk_bf16_f32 v59, v126, v127
	s_lshl_b64 s[36:37], s[22:23], 9
	v_lshl_add_u64 v[60:61], v[80:81], 0, s[36:37]
	global_store_dwordx4 v[60:61], v[56:59], off

; __device__ __forceinline__ unsigned pk2(float lo, float hi) { f32x2 v = {lo, hi}; bf16x2_t b = __builtin_convertvector(v, bf16x2_t); return __builtin_bit_cast(unsigned, b); }
; __device__ __forceinline__ float sigmoidf_(float x) { return __builtin_amdgcn_rcpf(1.f + __expf(-x)); }
; __device__ __forceinline__ void prep_even_phase(const Ctx& F) {
;     ...
;             if (lane < 32) {
;                 float cu[8], pv[8], o[8]; unpack8(rc[u], cu); unpack8(rpv[u], pv);
; #pragma unroll
;                 for (int e = 0; e < 8; ++e) { float v = cu[e] + (pv[e] - cu[e]) * mu8[e]; if (lane < 8) v = tanhf(v); else if (lane >= 16) v = sigmoidf_(v); o[e] = v; }
;                 *(u32x4*)(AP + (size_t)row * 256 + 8 * lane) = (u32x4){pk2(o[0], o[1]), pk2(o[2], o[3]), pk2(o[4], o[5]), pk2(o[6], o[7])};
;             }
.LBB0_393:
	s_waitcnt lgkmcnt(0)
	v_lshlrev_b32_e32 v108, 16, v40
	v_lshlrev_b32_e32 v109, 16, v44
	v_sub_f32_e32 v109, v109, v108
	v_fmac_f32_e32 v108, v0, v109
	v_and_b32_e32 v110, v106, v108
	v_mul_f32_e32 v110, v105, v110
	v_exp_f32_e32 v110, v110
	v_mul_f32_e32 v111, v108, v108
	v_add_f32_e32 v110, 1.0, v110
	v_rcp_f32_e32 v110, v110
	v_fmamk_f32 v112, v111, 0xbbbac73d, v86
	v_fmaak_f32 v112, v111, v112, 0xbd5c1c4e
	v_fmaak_f32 v112, v111, v112, 0x3e088382
	v_fmaak_f32 v112, v111, v112, 0xbeaaaa99
	v_mul_f32_e64 v112, |v108|, v112
	v_fma_f32 v112, v111, v112, |v108|
	v_fma_f32 v113, v110, -2.0, 1.0
	v_cmp_lt_f32_e64 vcc, |v108|, s48
	v_cndmask_b32_e64 v110, v108, v110, s[14:15]
	s_nop 0
	v_cndmask_b32_e32 v113, v113, v112, vcc
	v_bfi_b32 v113, s55, v113, v108
	v_cndmask_b32_e64 v120, v113, v110, s[12:13]
	v_and_b32_e32 v114, 0xffff0000, v40
	v_and_b32_e32 v115, 0xffff0000, v44
	v_sub_f32_e32 v115, v115, v114
	v_fmac_f32_e32 v114, v1, v115
	v_and_b32_e32 v116, v106, v114
	v_mul_f32_e32 v116, v105, v116
	v_exp_f32_e32 v116, v116
	v_mul_f32_e32 v117, v114, v114
	v_add_f32_e32 v116, 1.0, v116
	v_rcp_f32_e32 v116, v116
	v_fmamk_f32 v118, v117, 0xbbbac73d, v86
	v_fmaak_f32 v118, v117, v118, 0xbd5c1c4e
	v_fmaak_f32 v118, v117, v118, 0x3e088382
	v_fmaak_f32 v118, v117, v118, 0xbeaaaa99
	v_mul_f32_e64 v118, |v114|, v118
	v_fma_f32 v118, v117, v118, |v114|
	v_fma_f32 v119, v116, -2.0, 1.0
	v_cmp_lt_f32_e64 vcc, |v114|, s48
	v_cndmask_b32_e64 v116, v114, v116, s[14:15]
	s_nop 0
	v_cndmask_b32_e32 v119, v119, v118, vcc
	v_bfi_b32 v119, s55, v119, v114
	v_cndmask_b32_e64 v121, v119, v116, s[12:13]
	v_lshlrev_b32_e32 v108, 16, v41
	v_lshlrev_b32_e32 v109, 16, v45
	v_sub_f32_e32 v109, v109, v108
	v_fmac_f32_e32 v108, v2, v109
	v_and_b32_e32 v110, v106, v108
	v_mul_f32_e32 v110, v105, v110
	v_exp_f32_e32 v110, v110
	v_mul_f32_e32 v111, v108, v108
	v_add_f32_e32 v110, 1.0, v110
	v_rcp_f32_e32 v110, v110
	v_fmamk_f32 v112, v111, 0xbbbac73d, v86
	v_fmaak_f32 v112, v111, v112, 0xbd5c1c4e
	v_fmaak_f32 v112, v111, v112, 0x3e088382
	v_fmaak_f32 v112, v111, v112, 0xbeaaaa99
	v_mul_f32_e64 v112, |v108|, v112
	v_fma_f32 v112, v111, v112, |v108|
	v_fma_f32 v113, v110, -2.0, 1.0
	v_cmp_lt_f32_e64 vcc, |v108|, s48
	v_cndmask_b32_e64 v110, v108, v110, s[14:15]
	s_nop 0
	v_cndmask_b32_e32 v113, v113, v112, vcc
	v_bfi_b32 v113, s55, v113, v108
	v_cndmask_b32_e64 v122, v113, v110, s[12:13]
	v_and_b32_e32 v114, 0xffff0000, v41
	v_and_b32_e32 v115, 0xffff0000, v45
	v_sub_f32_e32 v115, v115, v114
	v_fmac_f32_e32 v114, v3, v115
	v_and_b32_e32 v116, v106, v114
	v_mul_f32_e32 v116, v105, v116
	v_exp_f32_e32 v116, v116
	v_mul_f32_e32 v117, v114, v114
	v_add_f32_e32 v116, 1.0, v116
	v_rcp_f32_e32 v116, v116
	v_fmamk_f32 v118, v117, 0xbbbac73d, v86
	v_fmaak_f32 v118, v117, v118, 0xbd5c1c4e
	v_fmaak_f32 v118, v117, v118, 0x3e088382
	v_fmaak_f32 v118, v117, v118, 0xbeaaaa99
	v_mul_f32_e64 v118, |v114|, v118
	v_fma_f32 v118, v117, v118, |v114|
	v_fma_f32 v119, v116, -2.0, 1.0
	v_cmp_lt_f32_e64 vcc, |v114|, s48
	v_cndmask_b32_e64 v116, v114, v116, s[14:15]
	s_nop 0
	v_cndmask_b32_e32 v119, v119, v118, vcc
	v_bfi_b32 v119, s55, v119, v114
	v_cndmask_b32_e64 v123, v119, v116, s[12:13]
	v_lshlrev_b32_e32 v108, 16, v42
	v_lshlrev_b32_e32 v109, 16, v46
	v_sub_f32_e32 v109, v109, v108
	v_fmac_f32_e32 v108, v4, v109
	v_and_b32_e32 v110, v106, v108
	v_mul_f32_e32 v110, v105, v110
	v_exp_f32_e32 v110, v110
	v_mul_f32_e32 v111, v108, v108
	v_add_f32_e32 v110, 1.0, v110
	v_rcp_f32_e32 v110, v110
	v_fmamk_f32 v112, v111, 0xbbbac73d, v86
	v_fmaak_f32 v112, v111, v112, 0xbd5c1c4e
	v_fmaak_f32 v112, v111, v112, 0x3e088382
	v_fmaak_f32 v112, v111, v112, 0xbeaaaa99
	v_mul_f32_e64 v112, |v108|, v112
	v_fma_f32 v112, v111, v112, |v108|
	v_fma_f32 v113, v110, -2.0, 1.0
	v_cmp_lt_f32_e64 vcc, |v108|, s48
	v_cndmask_b32_e64 v110, v108, v110, s[14:15]
	s_nop 0
	v_cndmask_b32_e32 v113, v113, v112, vcc
	v_bfi_b32 v113, s55, v113, v108
	v_cndmask_b32_e64 v124, v113, v110, s[12:13]
	v_and_b32_e32 v114, 0xffff0000, v42
	v_and_b32_e32 v115, 0xffff0000, v46
	v_sub_f32_e32 v115, v115, v114
	v_fmac_f32_e32 v114, v5, v115
	v_and_b32_e32 v116, v106, v114
	v_mul_f32_e32 v116, v105, v116
	v_exp_f32_e32 v116, v116
	v_mul_f32_e32 v117, v114, v114
	v_add_f32_e32 v116, 1.0, v116
	v_rcp_f32_e32 v116, v116
	v_fmamk_f32 v118, v117, 0xbbbac73d, v86
	v_fmaak_f32 v118, v117, v118, 0xbd5c1c4e
	v_fmaak_f32 v118, v117, v118, 0x3e088382
	v_fmaak_f32 v118, v117, v118, 0xbeaaaa99
	v_mul_f32_e64 v118, |v114|, v118
	v_fma_f32 v118, v117, v118, |v114|
	v_fma_f32 v119, v116, -2.0, 1.0
	v_cmp_lt_f32_e64 vcc, |v114|, s48
	v_cndmask_b32_e64 v116, v114, v116, s[14:15]
	s_nop 0
	v_cndmask_b32_e32 v119, v119, v118, vcc
	v_bfi_b32 v119, s55, v119, v114
	v_cndmask_b32_e64 v125, v119, v116, s[12:13]
	v_lshlrev_b32_e32 v108, 16, v43
	v_lshlrev_b32_e32 v109, 16, v47
	v_sub_f32_e32 v109, v109, v108
	v_fmac_f32_e32 v108, v6, v109
	v_and_b32_e32 v110, v106, v108
	v_mul_f32_e32 v110, v105, v110
	v_exp_f32_e32 v110, v110
	v_mul_f32_e32 v111, v108, v108
	v_add_f32_e32 v110, 1.0, v110
	v_rcp_f32_e32 v110, v110
	v_fmamk_f32 v112, v111, 0xbbbac73d, v86
	v_fmaak_f32 v112, v111, v112, 0xbd5c1c4e
	v_fmaak_f32 v112, v111, v112, 0x3e088382
	v_fmaak_f32 v112, v111, v112, 0xbeaaaa99
	v_mul_f32_e64 v112, |v108|, v112
	v_fma_f32 v112, v111, v112, |v108|
	v_fma_f32 v113, v110, -2.0, 1.0
	v_cmp_lt_f32_e64 vcc, |v108|, s48
	v_cndmask_b32_e64 v110, v108, v110, s[14:15]
	s_nop 0
	v_cndmask_b32_e32 v113, v113, v112, vcc
	v_bfi_b32 v113, s55, v113, v108
	v_cndmask_b32_e64 v126, v113, v110, s[12:13]
	v_and_b32_e32 v114, 0xffff0000, v43
	v_and_b32_e32 v115, 0xffff0000, v47
	v_sub_f32_e32 v115, v115, v114
	v_fmac_f32_e32 v114, v7, v115
	v_and_b32_e32 v116, v106, v114
	v_mul_f32_e32 v116, v105, v116
	v_exp_f32_e32 v116, v116
	v_mul_f32_e32 v117, v114, v114
	v_add_f32_e32 v116, 1.0, v116
	v_rcp_f32_e32 v116, v116
	v_fmamk_f32 v118, v117, 0xbbbac73d, v86
	v_fmaak_f32 v118, v117, v118, 0xbd5c1c4e
	v_fmaak_f32 v118, v117, v118, 0x3e088382
	v_fmaak_f32 v118, v117, v118, 0xbeaaaa99
	v_mul_f32_e64 v118, |v114|, v118
	v_fma_f32 v118, v117, v118, |v114|
	v_fma_f32 v119, v116, -2.0, 1.0
	v_cmp_lt_f32_e64 vcc, |v114|, s48
	v_cndmask_b32_e64 v116, v114, v116, s[14:15]
	s_nop 0
	v_cndmask_b32_e32 v119, v119, v118, vcc
	v_bfi_b32 v119, s55, v119, v114
	v_cndmask_b32_e64 v127, v119, v116, s[12:13]
	v_cvt_pk_bf16_f32 v40, v120, v121
	v_cvt_pk_bf16_f32 v41, v122, v123
	v_cvt_pk_bf16_f32 v42, v124, v125
	v_cvt_pk_bf16_f32 v43, v126, v127
	s_lshl_b64 s[34:35], s[34:35], 9
	v_lshl_add_u64 v[44:45], v[80:81], 0, s[34:35]
	global_store_dwordx4 v[44:45], v[40:43], off

; __device__ __forceinline__ unsigned pk2(float lo, float hi) { f32x2 v = {lo, hi}; bf16x2_t b = __builtin_convertvector(v, bf16x2_t); return __builtin_bit_cast(unsigned, b); }
; __device__ __forceinline__ float sigmoidf_(float x) { return __builtin_amdgcn_rcpf(1.f + __expf(-x)); }
; __device__ __forceinline__ void prep_even_phase(const Ctx& F) {
;     ...
;             if (lane < 32) {
;                 float cu[8], pv[8], o[8]; unpack8(rc[u], cu); unpack8(rpv[u], pv);
; #pragma unroll
;                 for (int e = 0; e < 8; ++e) { float v = cu[e] + (pv[e] - cu[e]) * mu8[e]; if (lane < 8) v = tanhf(v); else if (lane >= 16) v = sigmoidf_(v); o[e] = v; }
;                 *(u32x4*)(AP + (size_t)row * 256 + 8 * lane) = (u32x4){pk2(o[0], o[1]), pk2(o[2], o[3]), pk2(o[4], o[5]), pk2(o[6], o[7])};
;             }
.LBB0_463:
	s_waitcnt lgkmcnt(0)
	v_lshlrev_b32_e32 v108, 16, v24
	v_lshlrev_b32_e32 v109, 16, v28
	v_sub_f32_e32 v109, v109, v108
	v_fmac_f32_e32 v108, v0, v109
	v_and_b32_e32 v110, v106, v108
	v_mul_f32_e32 v110, v105, v110
	v_exp_f32_e32 v110, v110
	v_mul_f32_e32 v111, v108, v108
	v_add_f32_e32 v110, 1.0, v110
	v_rcp_f32_e32 v110, v110
	v_fmamk_f32 v112, v111, 0xbbbac73d, v86
	v_fmaak_f32 v112, v111, v112, 0xbd5c1c4e
	v_fmaak_f32 v112, v111, v112, 0x3e088382
	v_fmaak_f32 v112, v111, v112, 0xbeaaaa99
	v_mul_f32_e64 v112, |v108|, v112
	v_fma_f32 v112, v111, v112, |v108|
	v_fma_f32 v113, v110, -2.0, 1.0
	v_cmp_lt_f32_e64 vcc, |v108|, s48
	v_cndmask_b32_e64 v110, v108, v110, s[14:15]
	s_nop 0
	v_cndmask_b32_e32 v113, v113, v112, vcc
	v_bfi_b32 v113, s55, v113, v108
	v_cndmask_b32_e64 v120, v113, v110, s[12:13]
	v_and_b32_e32 v114, 0xffff0000, v24
	v_and_b32_e32 v115, 0xffff0000, v28
	v_sub_f32_e32 v115, v115, v114
	v_fmac_f32_e32 v114, v1, v115
	v_and_b32_e32 v116, v106, v114
	v_mul_f32_e32 v116, v105, v116
	v_exp_f32_e32 v116, v116
	v_mul_f32_e32 v117, v114, v114
	v_add_f32_e32 v116, 1.0, v116
	v_rcp_f32_e32 v116, v116
	v_fmamk_f32 v118, v117, 0xbbbac73d, v86
	v_fmaak_f32 v118, v117, v118, 0xbd5c1c4e
	v_fmaak_f32 v118, v117, v118, 0x3e088382
	v_fmaak_f32 v118, v117, v118, 0xbeaaaa99
	v_mul_f32_e64 v118, |v114|, v118
	v_fma_f32 v118, v117, v118, |v114|
	v_fma_f32 v119, v116, -2.0, 1.0
	v_cmp_lt_f32_e64 vcc, |v114|, s48
	v_cndmask_b32_e64 v116, v114, v116, s[14:15]
	s_nop 0
	v_cndmask_b32_e32 v119, v119, v118, vcc
	v_bfi_b32 v119, s55, v119, v114
	v_cndmask_b32_e64 v121, v119, v116, s[12:13]
	v_lshlrev_b32_e32 v108, 16, v25
	v_lshlrev_b32_e32 v109, 16, v29
	v_sub_f32_e32 v109, v109, v108
	v_fmac_f32_e32 v108, v2, v109
	v_and_b32_e32 v110, v106, v108
	v_mul_f32_e32 v110, v105, v110
	v_exp_f32_e32 v110, v110
	v_mul_f32_e32 v111, v108, v108
	v_add_f32_e32 v110, 1.0, v110
	v_rcp_f32_e32 v110, v110
	v_fmamk_f32 v112, v111, 0xbbbac73d, v86
	v_fmaak_f32 v112, v111, v112, 0xbd5c1c4e
	v_fmaak_f32 v112, v111, v112, 0x3e088382
	v_fmaak_f32 v112, v111, v112, 0xbeaaaa99
	v_mul_f32_e64 v112, |v108|, v112
	v_fma_f32 v112, v111, v112, |v108|
	v_fma_f32 v113, v110, -2.0, 1.0
	v_cmp_lt_f32_e64 vcc, |v108|, s48
	v_cndmask_b32_e64 v110, v108, v110, s[14:15]
	s_nop 0
	v_cndmask_b32_e32 v113, v113, v112, vcc
	v_bfi_b32 v113, s55, v113, v108
	v_cndmask_b32_e64 v122, v113, v110, s[12:13]
	v_and_b32_e32 v114, 0xffff0000, v25
	v_and_b32_e32 v115, 0xffff0000, v29
	v_sub_f32_e32 v115, v115, v114
	v_fmac_f32_e32 v114, v3, v115
	v_and_b32_e32 v116, v106, v114
	v_mul_f32_e32 v116, v105, v116
	v_exp_f32_e32 v116, v116
	v_mul_f32_e32 v117, v114, v114
	v_add_f32_e32 v116, 1.0, v116
	v_rcp_f32_e32 v116, v116
	v_fmamk_f32 v118, v117, 0xbbbac73d, v86
	v_fmaak_f32 v118, v117, v118, 0xbd5c1c4e
	v_fmaak_f32 v118, v117, v118, 0x3e088382
	v_fmaak_f32 v118, v117, v118, 0xbeaaaa99
	v_mul_f32_e64 v118, |v114|, v118
	v_fma_f32 v118, v117, v118, |v114|
	v_fma_f32 v119, v116, -2.0, 1.0
	v_cmp_lt_f32_e64 vcc, |v114|, s48
	v_cndmask_b32_e64 v116, v114, v116, s[14:15]
	s_nop 0
	v_cndmask_b32_e32 v119, v119, v118, vcc
	v_bfi_b32 v119, s55, v119, v114
	v_cndmask_b32_e64 v123, v119, v116, s[12:13]
	v_lshlrev_b32_e32 v108, 16, v26
	v_lshlrev_b32_e32 v109, 16, v30
	v_sub_f32_e32 v109, v109, v108
	v_fmac_f32_e32 v108, v4, v109
	v_and_b32_e32 v110, v106, v108
	v_mul_f32_e32 v110, v105, v110
	v_exp_f32_e32 v110, v110
	v_mul_f32_e32 v111, v108, v108
	v_add_f32_e32 v110, 1.0, v110
	v_rcp_f32_e32 v110, v110
	v_fmamk_f32 v112, v111, 0xbbbac73d, v86
	v_fmaak_f32 v112, v111, v112, 0xbd5c1c4e
	v_fmaak_f32 v112, v111, v112, 0x3e088382
	v_fmaak_f32 v112, v111, v112, 0xbeaaaa99
	v_mul_f32_e64 v112, |v108|, v112
	v_fma_f32 v112, v111, v112, |v108|
	v_fma_f32 v113, v110, -2.0, 1.0
	v_cmp_lt_f32_e64 vcc, |v108|, s48
	v_cndmask_b32_e64 v110, v108, v110, s[14:15]
	s_nop 0
	v_cndmask_b32_e32 v113, v113, v112, vcc
	v_bfi_b32 v113, s55, v113, v108
	v_cndmask_b32_e64 v124, v113, v110, s[12:13]
	v_and_b32_e32 v114, 0xffff0000, v26
	v_and_b32_e32 v115, 0xffff0000, v30
	v_sub_f32_e32 v115, v115, v114
	v_fmac_f32_e32 v114, v5, v115
	v_and_b32_e32 v116, v106, v114
	v_mul_f32_e32 v116, v105, v116
	v_exp_f32_e32 v116, v116
	v_mul_f32_e32 v117, v114, v114
	v_add_f32_e32 v116, 1.0, v116
	v_rcp_f32_e32 v116, v116
	v_fmamk_f32 v118, v117, 0xbbbac73d, v86
	v_fmaak_f32 v118, v117, v118, 0xbd5c1c4e
	v_fmaak_f32 v118, v117, v118, 0x3e088382
	v_fmaak_f32 v118, v117, v118, 0xbeaaaa99
	v_mul_f32_e64 v118, |v114|, v118
	v_fma_f32 v118, v117, v118, |v114|
	v_fma_f32 v119, v116, -2.0, 1.0
	v_cmp_lt_f32_e64 vcc, |v114|, s48
	v_cndmask_b32_e64 v116, v114, v116, s[14:15]
	s_nop 0
	v_cndmask_b32_e32 v119, v119, v118, vcc
	v_bfi_b32 v119, s55, v119, v114
	v_cndmask_b32_e64 v125, v119, v116, s[12:13]
	v_lshlrev_b32_e32 v108, 16, v27
	v_lshlrev_b32_e32 v109, 16, v31
	v_sub_f32_e32 v109, v109, v108
	v_fmac_f32_e32 v108, v6, v109
	v_and_b32_e32 v110, v106, v108
	v_mul_f32_e32 v110, v105, v110
	v_exp_f32_e32 v110, v110
	v_mul_f32_e32 v111, v108, v108
	v_add_f32_e32 v110, 1.0, v110
	v_rcp_f32_e32 v110, v110
	v_fmamk_f32 v112, v111, 0xbbbac73d, v86
	v_fmaak_f32 v112, v111, v112, 0xbd5c1c4e
	v_fmaak_f32 v112, v111, v112, 0x3e088382
	v_fmaak_f32 v112, v111, v112, 0xbeaaaa99
	v_mul_f32_e64 v112, |v108|, v112
	v_fma_f32 v112, v111, v112, |v108|
	v_fma_f32 v113, v110, -2.0, 1.0
	v_cmp_lt_f32_e64 vcc, |v108|, s48
	v_cndmask_b32_e64 v110, v108, v110, s[14:15]
	s_nop 0
	v_cndmask_b32_e32 v113, v113, v112, vcc
	v_bfi_b32 v113, s55, v113, v108
	v_cndmask_b32_e64 v126, v113, v110, s[12:13]
	v_and_b32_e32 v114, 0xffff0000, v27
	v_and_b32_e32 v115, 0xffff0000, v31
	v_sub_f32_e32 v115, v115, v114
	v_fmac_f32_e32 v114, v7, v115
	v_and_b32_e32 v116, v106, v114
	v_mul_f32_e32 v116, v105, v116
	v_exp_f32_e32 v116, v116
	v_mul_f32_e32 v117, v114, v114
	v_add_f32_e32 v116, 1.0, v116
	v_rcp_f32_e32 v116, v116
	v_fmamk_f32 v118, v117, 0xbbbac73d, v86
	v_fmaak_f32 v118, v117, v118, 0xbd5c1c4e
	v_fmaak_f32 v118, v117, v118, 0x3e088382
	v_fmaak_f32 v118, v117, v118, 0xbeaaaa99
	v_mul_f32_e64 v118, |v114|, v118
	v_fma_f32 v118, v117, v118, |v114|
	v_fma_f32 v119, v116, -2.0, 1.0
	v_cmp_lt_f32_e64 vcc, |v114|, s48
	v_cndmask_b32_e64 v116, v114, v116, s[14:15]
	s_nop 0
	v_cndmask_b32_e32 v119, v119, v118, vcc
	v_bfi_b32 v119, s55, v119, v114
	v_cndmask_b32_e64 v127, v119, v116, s[12:13]
	v_cvt_pk_bf16_f32 v24, v120, v121
	v_cvt_pk_bf16_f32 v25, v122, v123
	v_cvt_pk_bf16_f32 v26, v124, v125
	v_cvt_pk_bf16_f32 v27, v126, v127
	s_lshl_b64 s[30:31], s[30:31], 9
	v_lshl_add_u64 v[28:29], v[80:81], 0, s[30:31]
	global_store_dwordx4 v[28:29], v[24:27], off

; __device__ __forceinline__ unsigned pk2(float lo, float hi) { f32x2 v = {lo, hi}; bf16x2_t b = __builtin_convertvector(v, bf16x2_t); return __builtin_bit_cast(unsigned, b); }
; __device__ __forceinline__ float sigmoidf_(float x) { return __builtin_amdgcn_rcpf(1.f + __expf(-x)); }
; __device__ __forceinline__ void prep_even_phase(const Ctx& F) {
;     ...
;             if (lane < 32) {
;                 float cu[8], pv[8], o[8]; unpack8(rc[u], cu); unpack8(rpv[u], pv);
; #pragma unroll
;                 for (int e = 0; e < 8; ++e) { float v = cu[e] + (pv[e] - cu[e]) * mu8[e]; if (lane < 8) v = tanhf(v); else if (lane >= 16) v = sigmoidf_(v); o[e] = v; }
;                 *(u32x4*)(AP + (size_t)row * 256 + 8 * lane) = (u32x4){pk2(o[0], o[1]), pk2(o[2], o[3]), pk2(o[4], o[5]), pk2(o[6], o[7])};
;             }
.LBB0_533:
	s_waitcnt lgkmcnt(0)
	v_lshlrev_b32_e32 v108, 16, v8
	v_lshlrev_b32_e32 v109, 16, v12
	v_sub_f32_e32 v109, v109, v108
	v_fmac_f32_e32 v108, v0, v109
	v_and_b32_e32 v110, v106, v108
	v_mul_f32_e32 v110, v105, v110
	v_exp_f32_e32 v110, v110
	v_mul_f32_e32 v111, v108, v108
	v_add_f32_e32 v110, 1.0, v110
	v_rcp_f32_e32 v110, v110
	v_fmamk_f32 v112, v111, 0xbbbac73d, v86
	v_fmaak_f32 v112, v111, v112, 0xbd5c1c4e
	v_fmaak_f32 v112, v111, v112, 0x3e088382
	v_fmaak_f32 v112, v111, v112, 0xbeaaaa99
	v_mul_f32_e64 v112, |v108|, v112
	v_fma_f32 v112, v111, v112, |v108|
	v_fma_f32 v113, v110, -2.0, 1.0
	v_cmp_lt_f32_e64 vcc, |v108|, s48
	v_cndmask_b32_e64 v110, v108, v110, s[14:15]
	s_nop 0
	v_cndmask_b32_e32 v113, v113, v112, vcc
	v_bfi_b32 v113, s55, v113, v108
	v_cndmask_b32_e64 v120, v113, v110, s[12:13]
	v_and_b32_e32 v114, 0xffff0000, v8
	v_and_b32_e32 v115, 0xffff0000, v12
	v_sub_f32_e32 v115, v115, v114
	v_fmac_f32_e32 v114, v1, v115
	v_and_b32_e32 v116, v106, v114
	v_mul_f32_e32 v116, v105, v116
	v_exp_f32_e32 v116, v116
	v_mul_f32_e32 v117, v114, v114
	v_add_f32_e32 v116, 1.0, v116
	v_rcp_f32_e32 v116, v116
	v_fmamk_f32 v118, v117, 0xbbbac73d, v86
	v_fmaak_f32 v118, v117, v118, 0xbd5c1c4e
	v_fmaak_f32 v118, v117, v118, 0x3e088382
	v_fmaak_f32 v118, v117, v118, 0xbeaaaa99
	v_mul_f32_e64 v118, |v114|, v118
	v_fma_f32 v118, v117, v118, |v114|
	v_fma_f32 v119, v116, -2.0, 1.0
	v_cmp_lt_f32_e64 vcc, |v114|, s48
	v_cndmask_b32_e64 v116, v114, v116, s[14:15]
	s_nop 0
	v_cndmask_b32_e32 v119, v119, v118, vcc
	v_bfi_b32 v119, s55, v119, v114
	v_cndmask_b32_e64 v121, v119, v116, s[12:13]
	v_lshlrev_b32_e32 v108, 16, v9
	v_lshlrev_b32_e32 v109, 16, v13
	v_sub_f32_e32 v109, v109, v108
	v_fmac_f32_e32 v108, v2, v109
	v_and_b32_e32 v110, v106, v108
	v_mul_f32_e32 v110, v105, v110
	v_exp_f32_e32 v110, v110
	v_mul_f32_e32 v111, v108, v108
	v_add_f32_e32 v110, 1.0, v110
	v_rcp_f32_e32 v110, v110
	v_fmamk_f32 v112, v111, 0xbbbac73d, v86
	v_fmaak_f32 v112, v111, v112, 0xbd5c1c4e
	v_fmaak_f32 v112, v111, v112, 0x3e088382
	v_fmaak_f32 v112, v111, v112, 0xbeaaaa99
	v_mul_f32_e64 v112, |v108|, v112
	v_fma_f32 v112, v111, v112, |v108|
	v_fma_f32 v113, v110, -2.0, 1.0
	v_cmp_lt_f32_e64 vcc, |v108|, s48
	v_cndmask_b32_e64 v110, v108, v110, s[14:15]
	s_nop 0
	v_cndmask_b32_e32 v113, v113, v112, vcc
	v_bfi_b32 v113, s55, v113, v108
	v_cndmask_b32_e64 v122, v113, v110, s[12:13]
	v_and_b32_e32 v114, 0xffff0000, v9
	v_and_b32_e32 v115, 0xffff0000, v13
	v_sub_f32_e32 v115, v115, v114
	v_fmac_f32_e32 v114, v3, v115
	v_and_b32_e32 v116, v106, v114
	v_mul_f32_e32 v116, v105, v116
	v_exp_f32_e32 v116, v116
	v_mul_f32_e32 v117, v114, v114
	v_add_f32_e32 v116, 1.0, v116
	v_rcp_f32_e32 v116, v116
	v_fmamk_f32 v118, v117, 0xbbbac73d, v86
	v_fmaak_f32 v118, v117, v118, 0xbd5c1c4e
	v_fmaak_f32 v118, v117, v118, 0x3e088382
	v_fmaak_f32 v118, v117, v118, 0xbeaaaa99
	v_mul_f32_e64 v118, |v114|, v118
	v_fma_f32 v118, v117, v118, |v114|
	v_fma_f32 v119, v116, -2.0, 1.0
	v_cmp_lt_f32_e64 vcc, |v114|, s48
	v_cndmask_b32_e64 v116, v114, v116, s[14:15]
	s_nop 0
	v_cndmask_b32_e32 v119, v119, v118, vcc
	v_bfi_b32 v119, s55, v119, v114
	v_cndmask_b32_e64 v123, v119, v116, s[12:13]
	v_lshlrev_b32_e32 v108, 16, v10
	v_lshlrev_b32_e32 v109, 16, v14
	v_sub_f32_e32 v109, v109, v108
	v_fmac_f32_e32 v108, v4, v109
	v_and_b32_e32 v110, v106, v108
	v_mul_f32_e32 v110, v105, v110
	v_exp_f32_e32 v110, v110
	v_mul_f32_e32 v111, v108, v108
	v_add_f32_e32 v110, 1.0, v110
	v_rcp_f32_e32 v110, v110
	v_fmamk_f32 v112, v111, 0xbbbac73d, v86
	v_fmaak_f32 v112, v111, v112, 0xbd5c1c4e
	v_fmaak_f32 v112, v111, v112, 0x3e088382
	v_fmaak_f32 v112, v111, v112, 0xbeaaaa99
	v_mul_f32_e64 v112, |v108|, v112
	v_fma_f32 v112, v111, v112, |v108|
	v_fma_f32 v113, v110, -2.0, 1.0
	v_cmp_lt_f32_e64 vcc, |v108|, s48
	v_cndmask_b32_e64 v110, v108, v110, s[14:15]
	s_nop 0
	v_cndmask_b32_e32 v113, v113, v112, vcc
	v_bfi_b32 v113, s55, v113, v108
	v_cndmask_b32_e64 v124, v113, v110, s[12:13]
	v_and_b32_e32 v114, 0xffff0000, v10
	v_and_b32_e32 v115, 0xffff0000, v14
	v_sub_f32_e32 v115, v115, v114
	v_fmac_f32_e32 v114, v5, v115
	v_and_b32_e32 v116, v106, v114
	v_mul_f32_e32 v116, v105, v116
	v_exp_f32_e32 v116, v116
	v_mul_f32_e32 v117, v114, v114
	v_add_f32_e32 v116, 1.0, v116
	v_rcp_f32_e32 v116, v116
	v_fmamk_f32 v118, v117, 0xbbbac73d, v86
	v_fmaak_f32 v118, v117, v118, 0xbd5c1c4e
	v_fmaak_f32 v118, v117, v118, 0x3e088382
	v_fmaak_f32 v118, v117, v118, 0xbeaaaa99
	v_mul_f32_e64 v118, |v114|, v118
	v_fma_f32 v118, v117, v118, |v114|
	v_fma_f32 v119, v116, -2.0, 1.0
	v_cmp_lt_f32_e64 vcc, |v114|, s48
	v_cndmask_b32_e64 v116, v114, v116, s[14:15]
	s_nop 0
	v_cndmask_b32_e32 v119, v119, v118, vcc
	v_bfi_b32 v119, s55, v119, v114
	v_cndmask_b32_e64 v125, v119, v116, s[12:13]
	v_lshlrev_b32_e32 v108, 16, v11
	v_lshlrev_b32_e32 v109, 16, v15
	v_sub_f32_e32 v109, v109, v108
	v_fmac_f32_e32 v108, v6, v109
	v_and_b32_e32 v110, v106, v108
	v_mul_f32_e32 v110, v105, v110
	v_exp_f32_e32 v110, v110
	v_mul_f32_e32 v111, v108, v108
	v_add_f32_e32 v110, 1.0, v110
	v_rcp_f32_e32 v110, v110
	v_fmamk_f32 v112, v111, 0xbbbac73d, v86
	v_fmaak_f32 v112, v111, v112, 0xbd5c1c4e
	v_fmaak_f32 v112, v111, v112, 0x3e088382
	v_fmaak_f32 v112, v111, v112, 0xbeaaaa99
	v_mul_f32_e64 v112, |v108|, v112
	v_fma_f32 v112, v111, v112, |v108|
	v_fma_f32 v113, v110, -2.0, 1.0
	v_cmp_lt_f32_e64 vcc, |v108|, s48
	v_cndmask_b32_e64 v110, v108, v110, s[14:15]
	s_nop 0
	v_cndmask_b32_e32 v113, v113, v112, vcc
	v_bfi_b32 v113, s55, v113, v108
	v_cndmask_b32_e64 v126, v113, v110, s[12:13]
	v_and_b32_e32 v114, 0xffff0000, v11
	v_and_b32_e32 v115, 0xffff0000, v15
	v_sub_f32_e32 v115, v115, v114
	v_fmac_f32_e32 v114, v7, v115
	v_and_b32_e32 v116, v106, v114
	v_mul_f32_e32 v116, v105, v116
	v_exp_f32_e32 v116, v116
	v_mul_f32_e32 v117, v114, v114
	v_add_f32_e32 v116, 1.0, v116
	v_rcp_f32_e32 v116, v116
	v_fmamk_f32 v118, v117, 0xbbbac73d, v86
	v_fmaak_f32 v118, v117, v118, 0xbd5c1c4e
	v_fmaak_f32 v118, v117, v118, 0x3e088382
	v_fmaak_f32 v118, v117, v118, 0xbeaaaa99
	v_mul_f32_e64 v118, |v114|, v118
	v_fma_f32 v118, v117, v118, |v114|
	v_fma_f32 v119, v116, -2.0, 1.0
	v_cmp_lt_f32_e64 vcc, |v114|, s48
	v_cndmask_b32_e64 v116, v114, v116, s[14:15]
	s_nop 0
	v_cndmask_b32_e32 v119, v119, v118, vcc
	v_bfi_b32 v119, s55, v119, v114
	v_cndmask_b32_e64 v127, v119, v116, s[12:13]
	v_cvt_pk_bf16_f32 v8, v120, v121
	v_cvt_pk_bf16_f32 v9, v122, v123
	v_cvt_pk_bf16_f32 v10, v124, v125
	v_cvt_pk_bf16_f32 v11, v126, v127
	s_lshl_b64 s[28:29], s[28:29], 9
	v_lshl_add_u64 v[12:13], v[80:81], 0, s[28:29]
	global_store_dwordx4 v[12:13], v[8:11], off
	s_branch .LBB0_300

; #define LAS __attribute__((address_space(3)))
; __device__ __forceinline__ float bf2f(bf16_t v) { return __uint_as_float(((unsigned)v) << 16); }
; __device__ __forceinline__ bf16_t f2bf(float f) { return (bf16_t)(pk2(f, 0.f) & 0xffffu); }
; __device__ __forceinline__ float wave_sum_fast(float x) { x = reduce16(x); return (rl_(x, 0) + rl_(x, 16)) + (rl_(x, 32) + rl_(x, 48)); }
; __device__ __forceinline__ unsigned launder_(unsigned x) { asm volatile("" : "+v"(x)); return x; }
; __device__ __forceinline__ void rwkv_post_chunk(bf16_t* Y, const LAS unsigned char* Yp, const RwkvPostIn& in, int b, int h, int c, int w, int lane, float mu_v, float ln_w, float ln_b) {
;     const unsigned ulane = launder_((unsigned)lane);
; #pragma unroll
;     for (int j = 0; j < 4; ++j) {
;         const int tl = w + 8 * j; const size_t row = (size_t)b * S + c * 32 + tl;
;         const float yv = *(const LAS float*)(Yp + (tl * 64 + lane) * 4);
;         const float s1 = wave_sum_fast(yv), s2 = wave_sum_fast(yv * yv);
;         const float mean = s1 * (1.0f / 64.f), var = fmaxf(s2 * (1.0f / 64.f) - mean * mean, 0.f);
;         const float yn = (yv - mean) * (1.0f / sqrtf(var + 64e-5f)) * ln_w + ln_b;
;         float v = bf2f(in.pv0[j]); v += (bf2f(in.pv1[j]) - v) * mu_v;
;         (Y + row * D + 512 + h * 64)[ulane] = f2bf((yn + in.bon[j] * v) * bf2f(in.gq[j]));
;     }
; }
.LBB0_791:
	v_mov_b32_e32 v0, v71
	v_add_u32_e32 v2, s81, v80
	s_waitcnt lgkmcnt(0)
	s_barrier
	ds_read_b32 v2, v2 offset:26624
	v_add_u32_e32 v3, s83, v80
	v_add_u32_e32 v12, s85, v80
	v_add_u32_e32 v13, s87, v80
	ds_read_b32 v14, v3 offset:26624
	ds_read_b32 v15, v12 offset:26624
	ds_read_b32 v16, v13 offset:26624
	s_waitcnt lgkmcnt(3)
	v_add_f32_dpp v3, v2, v2 quad_perm:[1,0,3,2] row_mask:0xf bank_mask:0xf bound_ctrl:1
	s_lshl_b32 s4, s22, 7
	s_or_b32 s4, s4, 0x60
	v_add_f32_dpp v3, v3, v3 quad_perm:[2,3,0,1] row_mask:0xf bank_mask:0xf bound_ctrl:1
	s_waitcnt vmcnt(14)
	v_mov_b32_e32 v91, v94
	s_waitcnt vmcnt(5)
	v_mov_b32_e32 v88, v104
	v_add_f32_dpp v3, v3, v3 row_half_mirror row_mask:0xf bank_mask:0xf bound_ctrl:1
	v_mov_b32_e32 v85, v99
	v_mov_b32_e32 v82, v100
	v_add_f32_dpp v3, v3, v3 row_mirror row_mask:0xf bank_mask:0xf bound_ctrl:1
	v_mov_b32_e32 v92, v95
	v_readlane_b32 s6, v3, 16
	v_readlane_b32 s5, v3, 0
	s_waitcnt vmcnt(4)
	v_mov_b32_e32 v89, v103
	v_mov_b32_e32 v12, s6
	v_readlane_b32 s6, v3, 48
	v_add_f32_e32 v12, s5, v12
	v_readlane_b32 s5, v3, 32
	v_mov_b32_e32 v3, s6
	v_mov_b32_e32 v86, v96
	v_add_f32_e32 v3, s5, v3
	v_add_f32_e32 v3, v12, v3
	v_mul_f32_e32 v12, v2, v2
	v_mov_b32_e32 v83, v97
	v_mov_b32_e32 v93, v101
	v_mov_b32_dpp v12, v12 quad_perm:[1,0,3,2] row_mask:0xf bank_mask:0xf bound_ctrl:1
	v_fmac_f32_e32 v12, v2, v2
	v_fmac_f32_e32 v2, 0xbc800000, v3
	s_waitcnt vmcnt(3)
	v_mov_b32_e32 v90, v102
	v_add_f32_dpp v12, v12, v12 quad_perm:[2,3,0,1] row_mask:0xf bank_mask:0xf bound_ctrl:1
	v_mov_b32_e32 v87, v67
	v_mov_b32_e32 v84, v98
	v_add_f32_dpp v12, v12, v12 row_half_mirror row_mask:0xf bank_mask:0xf bound_ctrl:1
	s_nop 1
	v_add_f32_dpp v12, v12, v12 row_mirror row_mask:0xf bank_mask:0xf bound_ctrl:1
	s_nop 0
	v_readlane_b32 s6, v12, 16
	v_readlane_b32 s5, v12, 0
	s_nop 0
	v_mov_b32_e32 v13, s6
	v_readlane_b32 s6, v12, 48
	v_add_f32_e32 v13, s5, v13
	v_readlane_b32 s5, v12, 32
	v_mov_b32_e32 v12, s6
	s_add_u32 s6, s38, s4
	v_add_f32_e32 v12, s5, v12
	v_add_f32_e32 v12, v13, v12
	v_mul_f32_e32 v13, 0x3c800000, v3
	v_mul_f32_e32 v13, v13, v13
	v_fma_f32 v12, v12, s90, -v13
	v_max_f32_e32 v12, 0, v12
	v_add_f32_e32 v12, 0x3a27c5ac, v12
	v_rsq_f32_e32 v250, v12
	s_addc_u32 s7, s39, 0
	s_nop 0
	s_add_u32 s4, s6, s50
	s_addc_u32 s5, s7, 0
	s_lshl_b64 s[4:5], s[4:5], 11
	v_mov_b32_e32 v3, v250
	v_mul_f32_e32 v2, v2, v3
	v_lshlrev_b32_e32 v3, 16, v94
	v_lshlrev_b32_e32 v12, 16, v95
	v_sub_f32_e32 v12, v12, v3
	v_fma_f32 v2, v73, v2, v74
	v_fmac_f32_e32 v3, v72, v12
	v_fmac_f32_e32 v2, v61, v3
	v_lshlrev_b32_e32 v3, 16, v101
	v_mul_f32_e32 v2, v2, v3
	v_cvt_pk_bf16_f32 v17, v2, s0
	s_add_u32 s4, s71, s4
	s_waitcnt lgkmcnt(2)
	v_add_f32_dpp v2, v14, v14 quad_perm:[1,0,3,2] row_mask:0xf bank_mask:0xf bound_ctrl:1
	s_addc_u32 s5, s54, s5
	s_nop 0
	v_add_f32_dpp v2, v2, v2 quad_perm:[2,3,0,1] row_mask:0xf bank_mask:0xf bound_ctrl:1
	s_nop 1
	v_add_f32_dpp v2, v2, v2 row_half_mirror row_mask:0xf bank_mask:0xf bound_ctrl:1
	s_nop 1
	v_add_f32_dpp v2, v2, v2 row_mirror row_mask:0xf bank_mask:0xf bound_ctrl:1
	s_nop 0
	v_readlane_b32 s9, v2, 16
	v_readlane_b32 s8, v2, 0
	s_nop 0
	v_mov_b32_e32 v3, s9
	v_readlane_b32 s9, v2, 48
	v_add_f32_e32 v3, s8, v3
	v_readlane_b32 s8, v2, 32
	v_mov_b32_e32 v2, s9
	s_nop 0
	v_add_f32_e32 v2, s8, v2
	v_add_f32_e32 v18, v3, v2
	v_mul_f32_e32 v2, v14, v14
	s_nop 1
	v_mov_b32_dpp v2, v2 quad_perm:[1,0,3,2] row_mask:0xf bank_mask:0xf bound_ctrl:1
	v_fmac_f32_e32 v2, v14, v14
	v_fmac_f32_e32 v14, 0xbc800000, v18
	s_nop 0
	v_add_f32_dpp v2, v2, v2 quad_perm:[2,3,0,1] row_mask:0xf bank_mask:0xf bound_ctrl:1
	s_nop 1
	v_add_f32_dpp v2, v2, v2 row_half_mirror row_mask:0xf bank_mask:0xf bound_ctrl:1
	s_nop 1
	v_add_f32_dpp v2, v2, v2 row_mirror row_mask:0xf bank_mask:0xf bound_ctrl:1
	s_nop 0
	v_readlane_b32 s9, v2, 16
	v_readlane_b32 s8, v2, 0
	s_nop 0
	v_mov_b32_e32 v3, s9
	v_readlane_b32 s9, v2, 48
	v_add_f32_e32 v3, s8, v3
	v_readlane_b32 s8, v2, 32
	v_mov_b32_e32 v2, s9
	s_nop 0
	v_add_f32_e32 v2, s8, v2
	v_add_f32_e32 v2, v3, v2
	v_mul_f32_e32 v3, 0x3c800000, v18
	v_mul_f32_e32 v3, v3, v3
	v_fma_f32 v2, v2, s90, -v3
	v_max_f32_e32 v2, 0, v2
	v_add_f32_e32 v2, 0x3a27c5ac, v2
	v_rsq_f32_e32 v251, v2
	v_lshlrev_b64 v[2:3], 1, v[0:1]
	v_lshl_add_u64 v[12:13], s[4:5], 0, v[2:3]
	global_store_short v[12:13], v17, off offset:1024
	s_add_u32 s4, s6, s82
	s_addc_u32 s5, s7, 0
	s_lshl_b64 s[4:5], s[4:5], 11
	v_mov_b32_e32 v0, v251
	v_lshlrev_b32_e32 v12, 16, v104
	v_lshlrev_b32_e32 v13, 16, v103
	v_mul_f32_e32 v0, v14, v0
	v_sub_f32_e32 v13, v13, v12
	v_fma_f32 v0, v73, v0, v74
	v_fmac_f32_e32 v12, v72, v13
	s_waitcnt vmcnt(3)
; #define LAS __attribute__((address_space(3)))
; __device__ __forceinline__ float bf2f(bf16_t v) { return __uint_as_float(((unsigned)v) << 16); }
; __device__ __forceinline__ bf16_t f2bf(float f) { return (bf16_t)(pk2(f, 0.f) & 0xffffu); }
; __device__ __forceinline__ float wave_sum_fast(float x) { x = reduce16(x); return (rl_(x, 0) + rl_(x, 16)) + (rl_(x, 32) + rl_(x, 48)); }
; __device__ __forceinline__ unsigned launder_(unsigned x) { asm volatile("" : "+v"(x)); return x; }
; __device__ __forceinline__ void rwkv_post_chunk(bf16_t* Y, const LAS unsigned char* Yp, const RwkvPostIn& in, int b, int h, int c, int w, int lane, float mu_v, float ln_w, float ln_b) {
;     const unsigned ulane = launder_((unsigned)lane);
; #pragma unroll
;     for (int j = 0; j < 4; ++j) {
;         const int tl = w + 8 * j; const size_t row = (size_t)b * S + c * 32 + tl;
;         const float yv = *(const LAS float*)(Yp + (tl * 64 + lane) * 4);
;         const float s1 = wave_sum_fast(yv), s2 = wave_sum_fast(yv * yv);
;         const float mean = s1 * (1.0f / 64.f), var = fmaxf(s2 * (1.0f / 64.f) - mean * mean, 0.f);
;         const float yn = (yv - mean) * (1.0f / sqrtf(var + 64e-5f)) * ln_w + ln_b;
;         float v = bf2f(in.pv0[j]); v += (bf2f(in.pv1[j]) - v) * mu_v;
;         (Y + row * D + 512 + h * 64)[ulane] = f2bf((yn + in.bon[j] * v) * bf2f(in.gq[j]));
;     }
; }
	v_fmac_f32_e32 v0, v64, v12
	v_lshlrev_b32_e32 v12, 16, v102
	v_mul_f32_e32 v0, v0, v12
	s_add_u32 s4, s71, s4
	s_waitcnt lgkmcnt(1)
	v_add_f32_dpp v12, v15, v15 quad_perm:[1,0,3,2] row_mask:0xf bank_mask:0xf bound_ctrl:1
	s_addc_u32 s5, s54, s5
	v_cvt_pk_bf16_f32 v0, v0, s0
	v_add_f32_dpp v12, v12, v12 quad_perm:[2,3,0,1] row_mask:0xf bank_mask:0xf bound_ctrl:1
	s_nop 1
	v_add_f32_dpp v12, v12, v12 row_half_mirror row_mask:0xf bank_mask:0xf bound_ctrl:1
	s_nop 1
	v_add_f32_dpp v12, v12, v12 row_mirror row_mask:0xf bank_mask:0xf bound_ctrl:1
	s_nop 0
	v_readlane_b32 s9, v12, 16
	v_readlane_b32 s8, v12, 0
	s_nop 0
	v_mov_b32_e32 v13, s9
	v_readlane_b32 s9, v12, 48
	v_add_f32_e32 v13, s8, v13
	v_readlane_b32 s8, v12, 32
	v_mov_b32_e32 v12, s9
	s_nop 0
	v_add_f32_e32 v12, s8, v12
	v_add_f32_e32 v14, v13, v12
	v_mul_f32_e32 v12, v15, v15
	s_nop 1
	v_mov_b32_dpp v12, v12 quad_perm:[1,0,3,2] row_mask:0xf bank_mask:0xf bound_ctrl:1
	v_fmac_f32_e32 v12, v15, v15
	v_fmac_f32_e32 v15, 0xbc800000, v14
	s_nop 0
	v_add_f32_dpp v12, v12, v12 quad_perm:[2,3,0,1] row_mask:0xf bank_mask:0xf bound_ctrl:1
	s_nop 1
	v_add_f32_dpp v12, v12, v12 row_half_mirror row_mask:0xf bank_mask:0xf bound_ctrl:1
	s_nop 1
	v_add_f32_dpp v12, v12, v12 row_mirror row_mask:0xf bank_mask:0xf bound_ctrl:1
	s_nop 0
	v_readlane_b32 s9, v12, 16
	v_readlane_b32 s8, v12, 0
	s_nop 0
	v_mov_b32_e32 v13, s9
	v_readlane_b32 s9, v12, 48
	v_add_f32_e32 v13, s8, v13
	v_readlane_b32 s8, v12, 32
	v_mov_b32_e32 v12, s9
	s_nop 0
	v_add_f32_e32 v12, s8, v12
	v_add_f32_e32 v12, v13, v12
	v_mul_f32_e32 v13, 0x3c800000, v14
	v_mul_f32_e32 v13, v13, v13
	v_fma_f32 v12, v12, s90, -v13
	v_max_f32_e32 v12, 0, v12
	v_add_f32_e32 v12, 0x3a27c5ac, v12
	v_rsq_f32_e32 v252, v12
	v_lshl_add_u64 v[12:13], s[4:5], 0, v[2:3]
	global_store_short v[12:13], v0, off offset:1024
	s_add_u32 s4, s6, s84
	s_addc_u32 s5, s7, 0
	s_lshl_b64 s[4:5], s[4:5], 11
	v_mov_b32_e32 v0, v252
	v_lshlrev_b32_e32 v12, 16, v99
	v_lshlrev_b32_e32 v13, 16, v96
	v_mul_f32_e32 v0, v15, v0
	v_sub_f32_e32 v13, v13, v12
	v_fma_f32 v0, v73, v0, v74
	v_fmac_f32_e32 v12, v72, v13
	s_waitcnt vmcnt(3)
	v_fmac_f32_e32 v0, v65, v12
	v_lshlrev_b32_e32 v12, 16, v67
	v_mul_f32_e32 v0, v0, v12
	s_add_u32 s4, s71, s4
	s_waitcnt lgkmcnt(0)
	v_add_f32_dpp v12, v16, v16 quad_perm:[1,0,3,2] row_mask:0xf bank_mask:0xf bound_ctrl:1
	s_addc_u32 s5, s54, s5
	v_cvt_pk_bf16_f32 v0, v0, s0
	v_add_f32_dpp v12, v12, v12 quad_perm:[2,3,0,1] row_mask:0xf bank_mask:0xf bound_ctrl:1
	s_nop 1
	v_add_f32_dpp v12, v12, v12 row_half_mirror row_mask:0xf bank_mask:0xf bound_ctrl:1
	s_nop 1
	v_add_f32_dpp v12, v12, v12 row_mirror row_mask:0xf bank_mask:0xf bound_ctrl:1
	s_nop 0
	v_readlane_b32 s9, v12, 16
	v_readlane_b32 s8, v12, 0
	s_nop 0
	v_mov_b32_e32 v13, s9
	v_readlane_b32 s9, v12, 48
	v_add_f32_e32 v13, s8, v13
	v_readlane_b32 s8, v12, 32
	v_mov_b32_e32 v12, s9
	s_nop 0
	v_add_f32_e32 v12, s8, v12
	v_add_f32_e32 v14, v13, v12
	v_mul_f32_e32 v12, v16, v16
	s_nop 1
	v_mov_b32_dpp v12, v12 quad_perm:[1,0,3,2] row_mask:0xf bank_mask:0xf bound_ctrl:1
	v_fmac_f32_e32 v12, v16, v16
	v_fmac_f32_e32 v16, 0xbc800000, v14
	s_nop 0
	v_add_f32_dpp v12, v12, v12 quad_perm:[2,3,0,1] row_mask:0xf bank_mask:0xf bound_ctrl:1
	s_nop 1
	v_add_f32_dpp v12, v12, v12 row_half_mirror row_mask:0xf bank_mask:0xf bound_ctrl:1
	s_nop 1
	v_add_f32_dpp v12, v12, v12 row_mirror row_mask:0xf bank_mask:0xf bound_ctrl:1
	s_nop 0
	v_readlane_b32 s9, v12, 16
	v_readlane_b32 s8, v12, 0
	s_nop 0
	v_mov_b32_e32 v13, s9
	v_readlane_b32 s9, v12, 48
	v_add_f32_e32 v13, s8, v13
	v_readlane_b32 s8, v12, 32
	v_mov_b32_e32 v12, s9
	s_nop 0
	v_add_f32_e32 v12, s8, v12
	v_add_f32_e32 v12, v13, v12
	v_mul_f32_e32 v13, 0x3c800000, v14
	v_mul_f32_e32 v13, v13, v13
	v_fma_f32 v12, v12, s90, -v13
	v_max_f32_e32 v12, 0, v12
	v_add_f32_e32 v12, 0x3a27c5ac, v12
	v_rsq_f32_e32 v253, v12
	v_lshl_add_u64 v[12:13], s[4:5], 0, v[2:3]
	global_store_short v[12:13], v0, off offset:1024
	s_add_u32 s4, s6, s86
	s_addc_u32 s5, s7, 0
	s_lshl_b64 s[4:5], s[4:5], 11
	s_add_u32 s4, s71, s4
	s_addc_u32 s5, s54, s5
	s_add_i32 s22, s22, 1
	s_add_u32 s40, s40, 0x40000
	v_mov_b32_e32 v0, v253
	v_lshlrev_b32_e32 v12, 16, v100
	v_lshlrev_b32_e32 v13, 16, v97
	s_addc_u32 s41, s41, 0
	s_addk_i32 s42, 0x80
	v_mul_f32_e32 v0, v16, v0
	v_sub_f32_e32 v13, v13, v12
	s_add_u32 s56, s56, 0x60000
	v_fma_f32 v0, v73, v0, v74
	v_fmac_f32_e32 v12, v72, v13
	s_addc_u32 s57, s57, 0
	s_waitcnt vmcnt(3)
	v_fmac_f32_e32 v0, v66, v12
	v_lshlrev_b32_e32 v12, 16, v98
	s_add_u32 s58, s58, 0xa0000
	v_mul_f32_e32 v0, v0, v12
	s_addc_u32 s59, s59, 0
	v_cvt_pk_bf16_f32 v0, v0, s0
	v_lshl_add_u64 v[2:3], s[4:5], 0, v[2:3]
	s_cmp_eq_u32 s22, 16
	global_store_short v[2:3], v0, off offset:1024
	s_cbranch_scc1 .LBB0_789

; #define LAS __attribute__((address_space(3)))
; __device__ __forceinline__ unsigned launder_(unsigned x) { asm volatile("" : "+v"(x)); return x; }
; __device__ __forceinline__ void rwkv_chunked_bh(const Ctx& F, int b, int h) {
;     ...
;             const unsigned o128 = launder_((unsigned)(i * 128 + 16 * g)), o64 = launder_((unsigned)(i * 64 + 16 * g)), ulane = launder_((unsigned)lane);
; #pragma unroll
;             for (int q = 0; q < 2; ++q) { const int kt = 2 * kh + q;
;                 ng[q][0] = glb16(X + RX_NGT + 16 * kt * 128 + o128); ng[q][1] = glb16(X + RX_NGT + 16 * kt * 128 + 64 + o128);
;                 hf[q] = glb16(X + RX_HT + 16 * kt * 64 + o64); c4[q] = *(const f32x4*)(X + RX_CC + 16 * kt * 4 + (unsigned)(16 * g)); }
;             qf[0] = glb16(X + RX_QT + 16 * kh * 128 + o128); qf[1] = glb16(X + RX_QT + 16 * kh * 128 + 64 + o128);
;             wyf = glb16(X + RX_WYT + 16 * kh * 64 + o64); vf = glb16(X + RX_VT + 16 * vt * 64 + o64);
;             RwkvPostIn cur;
; #pragma unroll
;             for (int j = 0; j < 4; ++j) { const int t = c * 32 + w + 8 * j; const size_t row = (size_t)b * S + t; const bf16_t* p = proj + row * IN_EVEN_P + RW_OFF + 1024 + h * 64; const unsigned ul = ulane;
;                 cur.pv0[j] = p[ul]; cur.pv1[j] = t > 0 ? (p - IN_EVEN_P)[ul] : (bf16_t)0; cur.gq[j] = (LO + row * 1536 + 1024 + h * 64)[ul]; cur.bon[j] = *(const float*)(X + RX_BON + 4 * (w + 8 * j)); }
; #pragma unroll
;             for (int q = 0; q < 2; ++q) *(LAS u32x2*)(Ls + RB_SB + (16 * vt + i) * 144 + (16 * (2 * kh + q) + 4 * g) * 2) = (u32x2){pk2(sT[q][0], sT[q][1]), pk2(sT[q][2], sT[q][3])};
;             __syncthreads();
;             const bf16x8 bs0 = lds16(Ls + RB_SB + (16 * vt + i) * 144 + (8 * g) * 2), bs1 = lds16(Ls + RB_SB + (16 * vt + i) * 144 + (32 + 8 * g) * 2);
;             f32x4 y = MFMA16(qf[0], bs0, ((f32x4){0.f, 0.f, 0.f, 0.f})); y = MFMA16(qf[1], bs1, y); y = MFMA16(wyf, vf, y);
; #pragma unroll
;             for (int q = 0; q < 2; ++q) { f32x4 a = sT[q] * c4[q]; a = MFMA16(ng[q][0], bs0, a); a = MFMA16(ng[q][1], bs1, a); sT[q] = MFMA16(hf[q], vf, a); }
; #pragma unroll
;             for (int r = 0; r < 4; ++r) *(LAS float*)(Ls + RB_YL + ((16 * kh + 4 * g + r) * 64 + 16 * vt + i) * 4) = y[r];
;             if (cc > 0) rwkv_post_chunk(Y, L + ((cc - 1) & 1) * RBSTG + RB_YL, prv, b, h, c - 1, w, lane, mu_v, ln_w, ln_b);
.LBB0_838:
	s_bitcmp1_b32 s23, 0
	s_cselect_b32 s52, 0x4400, 0
	s_add_u32 s4, s46, s66
	s_addc_u32 s5, s47, s67
	v_lshl_add_u64 v[66:67], s[4:5], 0, v[66:67]
	v_add_co_u32_e32 v102, vcc, 0x32200000, v66
	s_add_u32 s4, s46, s6
	s_nop 0
	v_addc_co_u32_e32 v103, vcc, 0, v67, vcc
	v_add_co_u32_e32 v110, vcc, 0xc20a000, v64
	s_addc_u32 s5, s47, s7
	s_nop 0
	v_addc_co_u32_e32 v111, vcc, 0, v65, vcc
	v_add_co_u32_e32 v112, vcc, 0xc209000, v64
	s_nop 1
	v_addc_co_u32_e32 v113, vcc, 0, v65, vcc
	v_add_co_u32_e32 v114, vcc, 0x32206000, v66
	s_nop 1
	v_addc_co_u32_e32 v115, vcc, 0, v67, vcc
	v_add_co_u32_e32 v96, vcc, 0xc214000, v64
	s_nop 1
	v_addc_co_u32_e32 v97, vcc, 0, v65, vcc
	v_add_co_u32_e32 v100, vcc, 0xc213000, v64
	s_nop 1
	v_addc_co_u32_e32 v101, vcc, 0, v65, vcc
	v_add_co_u32_e32 v116, vcc, 0x3220c000, v66
	s_nop 1
	v_addc_co_u32_e32 v117, vcc, 0, v67, vcc
	v_add_co_u32_e32 v118, vcc, 0xc21e000, v64
	s_nop 1
	v_addc_co_u32_e32 v119, vcc, 0, v65, vcc
	v_add_co_u32_e32 v64, vcc, 0xc21d000, v64
	s_nop 1
	v_addc_co_u32_e32 v65, vcc, 0, v65, vcc
	v_add_co_u32_e32 v120, vcc, 0x32212000, v66
	s_nop 1
	v_addc_co_u32_e32 v121, vcc, 0, v67, vcc
	global_load_ushort v99, v[96:97], off offset:3392
	s_nop 0
	global_load_ushort v96, v[100:101], off offset:2368
	global_load_ushort v67, v[116:117], off offset:2048
	s_nop 0
	global_load_ushort v100, v[118:119], off offset:3392
	global_load_ushort v97, v[64:65], off offset:2368
	global_load_ushort v98, v[120:121], off offset:2048
	global_load_ushort v101, v[102:103], off offset:2048
	global_load_dword v61, v68, s[4:5] offset:2304
	global_load_ushort v104, v[110:111], off offset:3392
	s_nop 0
	global_load_ushort v103, v[112:113], off offset:2368
	global_load_ushort v102, v[114:115], off offset:2048
	global_load_dword v64, v68, s[4:5] offset:2336
	global_load_dword v65, v68, s[4:5] offset:2368
	global_load_dword v66, v68, s[4:5] offset:2400
	s_add_i32 s4, s52, 0
	v_add_u32_e32 v0, s4, v77
	v_add3_u32 v109, v0, v78, s80
	v_cvt_pk_bf16_f32 v110, v4, v5
	v_cvt_pk_bf16_f32 v111, v6, v7
	v_cvt_pk_bf16_f32 v112, v8, v9
	v_cvt_pk_bf16_f32 v113, v10, v11
	v_add_u32_e32 v0, v0, v60
	ds_write2_b64 v109, v[110:111], v[112:113] offset1:4
	s_waitcnt lgkmcnt(0)
	s_barrier
	ds_read_b128 v[110:113], v0
	ds_read_b128 v[114:117], v0 offset:64
	s_waitcnt vmcnt(20)
	v_pk_mul_f32 v[6:7], v[6:7], v[42:43]
	v_pk_mul_f32 v[4:5], v[4:5], v[40:41]
	s_waitcnt vmcnt(19)
	v_pk_mul_f32 v[10:11], v[10:11], v[38:39]
	v_pk_mul_f32 v[8:9], v[8:9], v[36:37]
	s_waitcnt vmcnt(18) lgkmcnt(1)
	v_mfma_f32_16x16x32_bf16 v[52:55], v[52:55], v[110:113], 0
	s_add_i32 s4, s4, s88
	v_add3_u32 v0, s4, v79, v81
	s_cmp_eq_u32 s23, 0
	v_mfma_f32_16x16x32_bf16 v[4:7], v[12:15], v[110:113], v[4:7]
	v_mfma_f32_16x16x32_bf16 v[8:11], v[20:23], v[110:113], v[8:11]
	s_waitcnt vmcnt(17) lgkmcnt(0)
	v_mfma_f32_16x16x32_bf16 v[48:51], v[48:51], v[114:117], v[52:55]
	v_mfma_f32_16x16x32_bf16 v[4:7], v[16:19], v[114:117], v[4:7]
	v_mfma_f32_16x16x32_bf16 v[8:11], v[24:27], v[114:117], v[8:11]
	s_waitcnt vmcnt(16)
	v_mfma_f32_16x16x32_bf16 v[4:7], v[32:35], v[44:47], v[4:7]
	v_mfma_f32_16x16x32_bf16 v[8:11], v[28:31], v[44:47], v[8:11]
	s_waitcnt vmcnt(15)
	v_mfma_f32_16x16x32_bf16 v[12:15], v[56:59], v[44:47], v[48:51]
	s_nop 7
	ds_write2st64_b32 v0, v12, v13 offset0:36 offset1:37
	ds_write2st64_b32 v0, v14, v15 offset0:38 offset1:39
	s_cbranch_scc1 .LBB0_840
	s_andn2_b32 s4, 1, s23
	s_mulk_i32 s4, 0x4400
	v_add_u32_e32 v13, s4, v80
	v_mov_b32_e32 v0, v71
	v_add_u32_e32 v12, s81, v13
	ds_read_b32 v12, v12 offset:9216
	v_add_u32_e32 v14, s83, v13
	v_add_u32_e32 v15, s85, v13
	v_add_u32_e32 v13, s87, v13
	ds_read_b32 v18, v14 offset:9216
	ds_read_b32 v15, v15 offset:9216
	ds_read_b32 v14, v13 offset:9216
	s_waitcnt lgkmcnt(3)
	v_add_f32_dpp v13, v12, v12 quad_perm:[1,0,3,2] row_mask:0xf bank_mask:0xf bound_ctrl:1
	s_nop 1
	v_add_f32_dpp v13, v13, v13 quad_perm:[2,3,0,1] row_mask:0xf bank_mask:0xf bound_ctrl:1
	s_nop 1
	v_add_f32_dpp v13, v13, v13 row_half_mirror row_mask:0xf bank_mask:0xf bound_ctrl:1
	s_nop 1
	v_add_f32_dpp v13, v13, v13 row_mirror row_mask:0xf bank_mask:0xf bound_ctrl:1
	s_nop 0
	v_readlane_b32 s5, v13, 16
	v_readlane_b32 s4, v13, 0
	s_nop 0
	v_mov_b32_e32 v16, s5
	v_readlane_b32 s5, v13, 48
	v_add_f32_e32 v16, s4, v16
	v_readlane_b32 s4, v13, 32
	v_mov_b32_e32 v13, s5
	s_nop 0
	v_add_f32_e32 v13, s4, v13
	v_add_f32_e32 v13, v16, v13
	v_mul_f32_e32 v16, v12, v12
	s_nop 1
	v_mov_b32_dpp v16, v16 quad_perm:[1,0,3,2] row_mask:0xf bank_mask:0xf bound_ctrl:1
	v_fmac_f32_e32 v16, v12, v12
	v_fmac_f32_e32 v12, 0xbc800000, v13
	s_nop 0
	v_add_f32_dpp v16, v16, v16 quad_perm:[2,3,0,1] row_mask:0xf bank_mask:0xf bound_ctrl:1
	s_nop 1
	v_add_f32_dpp v16, v16, v16 row_half_mirror row_mask:0xf bank_mask:0xf bound_ctrl:1
	s_nop 1
	v_add_f32_dpp v16, v16, v16 row_mirror row_mask:0xf bank_mask:0xf bound_ctrl:1
	s_nop 0
	v_readlane_b32 s5, v16, 16
	v_readlane_b32 s4, v16, 0
	s_nop 0
	v_mov_b32_e32 v17, s5
	v_readlane_b32 s5, v16, 48
	v_add_f32_e32 v17, s4, v17
	v_readlane_b32 s4, v16, 32
	v_mov_b32_e32 v16, s5
	s_nop 0
	v_add_f32_e32 v16, s4, v16
	v_add_f32_e32 v16, v17, v16
	v_mul_f32_e32 v17, 0x3c800000, v13
	v_mul_f32_e32 v17, v17, v17
	v_fma_f32 v16, v16, s90, -v17
	v_max_f32_e32 v16, 0, v16
	v_add_f32_e32 v16, 0x3a27c5ac, v16
	v_rsq_f32_e32 v250, v16
	s_add_u32 s4, s46, s68
	v_mov_b32_e32 v13, v250
	v_mul_f32_e32 v12, v12, v13
	v_lshlrev_b32_e32 v13, 16, v91
	v_lshlrev_b32_e32 v16, 16, v92
	v_sub_f32_e32 v16, v16, v13
	v_fma_f32 v12, v73, v12, v74
	v_fmac_f32_e32 v13, v72, v16
	v_fmac_f32_e32 v12, v13, v108
	v_lshlrev_b32_e32 v13, 16, v93
	v_mul_f32_e32 v12, v12, v13
	v_cvt_pk_bf16_f32 v19, v12, s0
	s_waitcnt lgkmcnt(2)
; #define LAS __attribute__((address_space(3)))
; __device__ __forceinline__ float bf2f(bf16_t v) { return __uint_as_float(((unsigned)v) << 16); }
; __device__ __forceinline__ bf16_t f2bf(float f) { return (bf16_t)(pk2(f, 0.f) & 0xffffu); }
; __device__ __forceinline__ float wave_sum_fast(float x) { x = reduce16(x); return (rl_(x, 0) + rl_(x, 16)) + (rl_(x, 32) + rl_(x, 48)); }
; __device__ __forceinline__ void rwkv_post_chunk(bf16_t* Y, const LAS unsigned char* Yp, const RwkvPostIn& in, int b, int h, int c, int w, int lane, float mu_v, float ln_w, float ln_b) {
;     ...
;     for (int j = 0; j < 4; ++j) {
;         const int tl = w + 8 * j; const size_t row = (size_t)b * S + c * 32 + tl;
;         const float yv = *(const LAS float*)(Yp + (tl * 64 + lane) * 4);
;         const float s1 = wave_sum_fast(yv), s2 = wave_sum_fast(yv * yv);
;         const float mean = s1 * (1.0f / 64.f), var = fmaxf(s2 * (1.0f / 64.f) - mean * mean, 0.f);
;         const float yn = (yv - mean) * (1.0f / sqrtf(var + 64e-5f)) * ln_w + ln_b;
;         float v = bf2f(in.pv0[j]); v += (bf2f(in.pv1[j]) - v) * mu_v;
;         (Y + row * D + 512 + h * 64)[ulane] = f2bf((yn + in.bon[j] * v) * bf2f(in.gq[j]));
	v_add_f32_dpp v12, v18, v18 quad_perm:[1,0,3,2] row_mask:0xf bank_mask:0xf bound_ctrl:1
	s_nop 1
	v_add_f32_dpp v12, v12, v12 quad_perm:[2,3,0,1] row_mask:0xf bank_mask:0xf bound_ctrl:1
	s_nop 1
	v_add_f32_dpp v12, v12, v12 row_half_mirror row_mask:0xf bank_mask:0xf bound_ctrl:1
	s_nop 1
	v_add_f32_dpp v12, v12, v12 row_mirror row_mask:0xf bank_mask:0xf bound_ctrl:1
	s_nop 0
	v_readlane_b32 s52, v12, 16
	v_readlane_b32 s5, v12, 0
	s_nop 0
	v_mov_b32_e32 v13, s52
	v_readlane_b32 s52, v12, 48
	v_add_f32_e32 v13, s5, v13
	v_readlane_b32 s5, v12, 32
	v_mov_b32_e32 v12, s52
	s_nop 0
	v_add_f32_e32 v12, s5, v12
	v_add_f32_e32 v20, v13, v12
	v_mul_f32_e32 v12, v18, v18
	s_nop 1
	v_mov_b32_dpp v12, v12 quad_perm:[1,0,3,2] row_mask:0xf bank_mask:0xf bound_ctrl:1
	v_fmac_f32_e32 v12, v18, v18
	v_fmac_f32_e32 v18, 0xbc800000, v20
	s_nop 0
	v_add_f32_dpp v12, v12, v12 quad_perm:[2,3,0,1] row_mask:0xf bank_mask:0xf bound_ctrl:1
	s_nop 1
	v_add_f32_dpp v12, v12, v12 row_half_mirror row_mask:0xf bank_mask:0xf bound_ctrl:1
	s_nop 1
	v_add_f32_dpp v12, v12, v12 row_mirror row_mask:0xf bank_mask:0xf bound_ctrl:1
	s_nop 0
	v_readlane_b32 s52, v12, 16
	v_readlane_b32 s5, v12, 0
	s_nop 0
	v_mov_b32_e32 v13, s52
	v_readlane_b32 s52, v12, 48
	v_add_f32_e32 v13, s5, v13
	v_readlane_b32 s5, v12, 32
	v_mov_b32_e32 v12, s52
	s_mov_b32 s52, 0x41f0000
	v_add_f32_e32 v12, s5, v12
	v_add_f32_e32 v12, v13, v12
	v_mul_f32_e32 v13, 0x3c800000, v20
	v_mul_f32_e32 v13, v13, v13
	v_fma_f32 v12, v12, s90, -v13
	v_max_f32_e32 v12, 0, v12
	v_add_f32_e32 v12, 0x3a27c5ac, v12
	v_rsq_f32_e32 v251, v12
	s_addc_u32 s5, s47, s69
	s_nop 0
	v_lshl_add_u64 v[12:13], v[0:1], 1, s[4:5]
	v_add_co_u32_e32 v16, vcc, s52, v12
	s_mov_b32 s52, 0x41f4000
	s_nop 0
	v_addc_co_u32_e32 v17, vcc, 0, v13, vcc
	global_store_short v[16:17], v19, off offset:1024
	v_mov_b32_e32 v0, v251
	v_lshlrev_b32_e32 v16, 16, v88
	v_lshlrev_b32_e32 v17, 16, v89
	v_sub_f32_e32 v17, v17, v16
	v_fmac_f32_e32 v16, v72, v17
	v_mul_f32_e32 v0, v18, v0
	s_waitcnt lgkmcnt(1)
	v_add_f32_dpp v17, v15, v15 quad_perm:[1,0,3,2] row_mask:0xf bank_mask:0xf bound_ctrl:1
	v_fma_f32 v0, v73, v0, v74
	v_fmac_f32_e32 v0, v16, v107
	v_add_f32_dpp v17, v17, v17 quad_perm:[2,3,0,1] row_mask:0xf bank_mask:0xf bound_ctrl:1
	v_lshlrev_b32_e32 v16, 16, v90
	v_mul_f32_e32 v0, v0, v16
	v_add_f32_dpp v17, v17, v17 row_half_mirror row_mask:0xf bank_mask:0xf bound_ctrl:1
	v_cvt_pk_bf16_f32 v0, v0, s0
	s_nop 0
	v_add_f32_dpp v17, v17, v17 row_mirror row_mask:0xf bank_mask:0xf bound_ctrl:1
	s_nop 0
	v_readlane_b32 s5, v17, 16
	v_readlane_b32 s4, v17, 0
	s_nop 0
	v_mov_b32_e32 v18, s5
	v_readlane_b32 s5, v17, 48
	v_add_f32_e32 v18, s4, v18
	v_readlane_b32 s4, v17, 32
	v_mov_b32_e32 v17, s5
	s_nop 0
	v_add_f32_e32 v17, s4, v17
	v_add_f32_e32 v18, v18, v17
	v_mul_f32_e32 v17, v15, v15
	s_nop 1
	v_mov_b32_dpp v17, v17 quad_perm:[1,0,3,2] row_mask:0xf bank_mask:0xf bound_ctrl:1
	v_fmac_f32_e32 v17, v15, v15
	v_fmac_f32_e32 v15, 0xbc800000, v18
	s_nop 0
	v_add_f32_dpp v17, v17, v17 quad_perm:[2,3,0,1] row_mask:0xf bank_mask:0xf bound_ctrl:1
	s_nop 1
	v_add_f32_dpp v17, v17, v17 row_half_mirror row_mask:0xf bank_mask:0xf bound_ctrl:1
	s_nop 1
	v_add_f32_dpp v17, v17, v17 row_mirror row_mask:0xf bank_mask:0xf bound_ctrl:1
	s_nop 0
	v_readlane_b32 s5, v17, 16
	v_readlane_b32 s4, v17, 0
	s_nop 0
	v_mov_b32_e32 v19, s5
	v_readlane_b32 s5, v17, 48
	v_add_f32_e32 v19, s4, v19
	v_readlane_b32 s4, v17, 32
	v_mov_b32_e32 v17, s5
	s_nop 0
	v_add_f32_e32 v17, s4, v17
	v_add_f32_e32 v17, v19, v17
	v_mul_f32_e32 v19, 0x3c800000, v18
	v_mul_f32_e32 v19, v19, v19
	v_fma_f32 v17, v17, s90, -v19
	v_max_f32_e32 v17, 0, v17
	v_add_f32_e32 v17, 0x3a27c5ac, v17
	v_rsq_f32_e32 v252, v17
	v_add_co_u32_e32 v16, vcc, s52, v12
	s_mov_b32 s52, 0x41f8000
	s_nop 0
	v_addc_co_u32_e32 v17, vcc, 0, v13, vcc
	global_store_short v[16:17], v0, off offset:1024
	v_mov_b32_e32 v0, v252
	v_mul_f32_e32 v0, v15, v0
	v_lshlrev_b32_e32 v15, 16, v85
	v_lshlrev_b32_e32 v16, 16, v86
	v_sub_f32_e32 v16, v16, v15
	v_fmac_f32_e32 v15, v72, v16
	v_fma_f32 v0, v73, v0, v74
	s_waitcnt lgkmcnt(0)
	v_add_f32_dpp v16, v14, v14 quad_perm:[1,0,3,2] row_mask:0xf bank_mask:0xf bound_ctrl:1
	v_fmac_f32_e32 v0, v15, v106
	v_lshlrev_b32_e32 v15, 16, v87
	v_add_f32_dpp v16, v16, v16 quad_perm:[2,3,0,1] row_mask:0xf bank_mask:0xf bound_ctrl:1
	v_mul_f32_e32 v0, v0, v15
	v_cvt_pk_bf16_f32 v0, v0, s0
	v_add_f32_dpp v16, v16, v16 row_half_mirror row_mask:0xf bank_mask:0xf bound_ctrl:1
	s_nop 1
	v_add_f32_dpp v16, v16, v16 row_mirror row_mask:0xf bank_mask:0xf bound_ctrl:1
	s_nop 0
	v_readlane_b32 s5, v16, 16
	v_readlane_b32 s4, v16, 0
	s_nop 0
	v_mov_b32_e32 v17, s5
	v_readlane_b32 s5, v16, 48
	v_add_f32_e32 v17, s4, v17
	v_readlane_b32 s4, v16, 32
	v_mov_b32_e32 v16, s5
	s_nop 0
	v_add_f32_e32 v16, s4, v16
	v_add_f32_e32 v18, v17, v16
	v_mul_f32_e32 v16, v14, v14
	s_nop 1
	v_mov_b32_dpp v16, v16 quad_perm:[1,0,3,2] row_mask:0xf bank_mask:0xf bound_ctrl:1
	v_fmac_f32_e32 v16, v14, v14
	v_fmac_f32_e32 v14, 0xbc800000, v18
	s_nop 0
	v_add_f32_dpp v16, v16, v16 quad_perm:[2,3,0,1] row_mask:0xf bank_mask:0xf bound_ctrl:1
	s_nop 1
	v_add_f32_dpp v16, v16, v16 row_half_mirror row_mask:0xf bank_mask:0xf bound_ctrl:1
	s_nop 1
	v_add_f32_dpp v16, v16, v16 row_mirror row_mask:0xf bank_mask:0xf bound_ctrl:1
	s_nop 0
	v_readlane_b32 s5, v16, 16
	v_readlane_b32 s4, v16, 0
	s_nop 0
	v_mov_b32_e32 v17, s5
	v_readlane_b32 s5, v16, 48
	v_add_f32_e32 v17, s4, v17
	v_readlane_b32 s4, v16, 32
	v_mov_b32_e32 v16, s5
	s_nop 0
	v_add_f32_e32 v16, s4, v16
	v_add_f32_e32 v16, v17, v16
	v_mul_f32_e32 v17, 0x3c800000, v18
	v_mul_f32_e32 v17, v17, v17
	v_fma_f32 v16, v16, s90, -v17
	v_max_f32_e32 v16, 0, v16
	v_add_f32_e32 v16, 0x3a27c5ac, v16
	v_rsq_f32_e32 v253, v16
	v_add_co_u32_e32 v16, vcc, s52, v12
	s_nop 1
	v_addc_co_u32_e32 v17, vcc, 0, v13, vcc
	global_store_short v[16:17], v0, off offset:1024
	v_mov_b32_e32 v0, v253
	v_mul_f32_e32 v0, v14, v0
	v_lshlrev_b32_e32 v14, 16, v82
	v_lshlrev_b32_e32 v15, 16, v83
	v_sub_f32_e32 v15, v15, v14
	v_fma_f32 v0, v73, v0, v74
	v_fmac_f32_e32 v14, v72, v15
	v_fmac_f32_e32 v0, v14, v105
	v_lshlrev_b32_e32 v14, 16, v84
	v_mul_f32_e32 v0, v0, v14
	v_add_co_u32_e32 v12, vcc, 0x41fc000, v12
	v_cvt_pk_bf16_f32 v0, v0, s0
	s_nop 0
	v_addc_co_u32_e32 v13, vcc, 0, v13, vcc
	global_store_short v[12:13], v0, off offset:1024
